# adaLN GEMV inner loop rewritten: all 32 weight loads of a pass issued up front, S reads double-buffered one row ahead (9 LDS reads in flight instead of 1-3), same f32 math
# speedup vs baseline: 1.0030x; 1.0030x over previous
.LBB0_519:
	v_lshl_add_u32 v20, s1, 3, v66
	v_lshl_or_b32 v22, s1, 1, v65
	v_add_u32_e32 v21, 0x10000, v20
	v_mad_i64_i32 v[24:25], s[14:15], v22, s33, v[2:3]
	s_mov_b32 s15, 0
	global_load_dword v28, v[24:25], off
	s_mov_b32 s14, 0xc000
	v_lshl_add_u64 v[62:63], v[24:25], 0, s[14:15]
	global_load_dword v29, v[62:63], off
	s_mov_b32 s14, 0x18000
	v_lshl_add_u64 v[60:61], v[24:25], 0, s[14:15]
	global_load_dword v30, v[60:61], off
	s_mov_b32 s14, 0x24000
	v_lshl_add_u64 v[62:63], v[24:25], 0, s[14:15]
	global_load_dword v31, v[62:63], off
	v_add_u32_e32 v23, 0, v20
	ds_read2st64_b32 v[130:131], v23 offset1:16
	ds_read2st64_b32 v[132:133], v23 offset0:32 offset1:48
	ds_read2st64_b32 v[134:135], v23 offset0:64 offset1:80
	ds_read2st64_b32 v[136:137], v23 offset0:96 offset1:112
	ds_read2st64_b32 v[138:139], v23 offset0:128 offset1:144
	ds_read2st64_b32 v[140:141], v23 offset0:160 offset1:176
	ds_read2st64_b32 v[142:143], v23 offset0:192 offset1:208
	ds_read2st64_b32 v[144:145], v23 offset0:224 offset1:240
	ds_read_b32 v146, v21
	s_mov_b32 s14, 0x30000
	v_lshl_add_u64 v[60:61], v[24:25], 0, s[14:15]
	global_load_dword v32, v[60:61], off
	s_mov_b32 s14, 0x3c000
	v_lshl_add_u64 v[62:63], v[24:25], 0, s[14:15]
	global_load_dword v33, v[62:63], off
	s_mov_b32 s14, 0x48000
	v_lshl_add_u64 v[60:61], v[24:25], 0, s[14:15]
	global_load_dword v34, v[60:61], off
	s_mov_b32 s14, 0x54000
	v_lshl_add_u64 v[62:63], v[24:25], 0, s[14:15]
	global_load_dword v35, v[62:63], off
	s_mov_b32 s14, 0x60000
	v_lshl_add_u64 v[60:61], v[24:25], 0, s[14:15]
	global_load_dword v36, v[60:61], off
	s_mov_b32 s14, 0x6c000
	v_lshl_add_u64 v[62:63], v[24:25], 0, s[14:15]
	global_load_dword v37, v[62:63], off
	s_mov_b32 s14, 0x78000
	v_lshl_add_u64 v[60:61], v[24:25], 0, s[14:15]
	global_load_dword v38, v[60:61], off
	s_mov_b32 s14, 0x84000
	v_lshl_add_u64 v[62:63], v[24:25], 0, s[14:15]
	global_load_dword v39, v[62:63], off
	s_mov_b32 s14, 0x90000
	v_lshl_add_u64 v[60:61], v[24:25], 0, s[14:15]
	global_load_dword v40, v[60:61], off
	s_mov_b32 s14, 0x9c000
	v_lshl_add_u64 v[62:63], v[24:25], 0, s[14:15]
	global_load_dword v41, v[62:63], off
	s_mov_b32 s14, 0xa8000
	v_lshl_add_u64 v[60:61], v[24:25], 0, s[14:15]
	global_load_dword v42, v[60:61], off
	s_mov_b32 s14, 0xb4000
	v_lshl_add_u64 v[62:63], v[24:25], 0, s[14:15]
	global_load_dword v43, v[62:63], off
	s_mov_b32 s14, 0xc0000
	v_lshl_add_u64 v[60:61], v[24:25], 0, s[14:15]
	global_load_dword v44, v[60:61], off
	s_mov_b32 s14, 0xcc000
	v_lshl_add_u64 v[62:63], v[24:25], 0, s[14:15]
	global_load_dword v45, v[62:63], off
	s_mov_b32 s14, 0xd8000
	v_lshl_add_u64 v[60:61], v[24:25], 0, s[14:15]
	global_load_dword v46, v[60:61], off
	s_mov_b32 s14, 0xe4000
	v_lshl_add_u64 v[62:63], v[24:25], 0, s[14:15]
	global_load_dword v47, v[62:63], off
	s_mov_b32 s14, 0xf0000
	v_lshl_add_u64 v[60:61], v[24:25], 0, s[14:15]
	global_load_dword v48, v[60:61], off
	s_mov_b32 s14, 0xfc000
	v_lshl_add_u64 v[62:63], v[24:25], 0, s[14:15]
	global_load_dword v49, v[62:63], off
	s_mov_b32 s14, 0x108000
	v_lshl_add_u64 v[60:61], v[24:25], 0, s[14:15]
	global_load_dword v50, v[60:61], off
	s_mov_b32 s14, 0x114000
	v_lshl_add_u64 v[62:63], v[24:25], 0, s[14:15]
	global_load_dword v51, v[62:63], off
	s_mov_b32 s14, 0x120000
	v_lshl_add_u64 v[60:61], v[24:25], 0, s[14:15]
	global_load_dword v52, v[60:61], off
	s_mov_b32 s14, 0x12c000
	v_lshl_add_u64 v[62:63], v[24:25], 0, s[14:15]
	global_load_dword v53, v[62:63], off
	s_mov_b32 s14, 0x138000
	v_lshl_add_u64 v[60:61], v[24:25], 0, s[14:15]
	global_load_dword v54, v[60:61], off
	s_mov_b32 s14, 0x144000
	v_lshl_add_u64 v[62:63], v[24:25], 0, s[14:15]
	global_load_dword v55, v[62:63], off
	s_mov_b32 s14, 0x150000
	v_lshl_add_u64 v[60:61], v[24:25], 0, s[14:15]
	global_load_dword v56, v[60:61], off
	s_mov_b32 s14, 0x15c000
	v_lshl_add_u64 v[62:63], v[24:25], 0, s[14:15]
	global_load_dword v57, v[62:63], off
	s_mov_b32 s14, 0x168000
	v_lshl_add_u64 v[60:61], v[24:25], 0, s[14:15]
	global_load_dword v58, v[60:61], off
	s_mov_b32 s14, 0x174000
	v_lshl_add_u64 v[62:63], v[24:25], 0, s[14:15]
	global_load_dword v59, v[62:63], off
	v_add_u32_e32 v26, 8, v20
	ds_read2st64_b32 v[70:71], v26 offset1:16
	ds_read2st64_b32 v[72:73], v26 offset0:32 offset1:48
	ds_read2st64_b32 v[74:75], v26 offset0:64 offset1:80
	ds_read2st64_b32 v[76:77], v26 offset0:96 offset1:112
	ds_read2st64_b32 v[78:79], v26 offset0:128 offset1:144
	ds_read2st64_b32 v[80:81], v26 offset0:160 offset1:176
	ds_read2st64_b32 v[82:83], v26 offset0:192 offset1:208
	ds_read2st64_b32 v[84:85], v26 offset0:224 offset1:240
	ds_read_b32 v86, v21 offset:8
	s_waitcnt vmcnt(31) lgkmcnt(9)
	v_pk_fma_f32 v[4:5], v[28:29], v[130:131], v[4:5] op_sel_hi:[0,1,1]
	v_pk_fma_f32 v[6:7], v[28:29], v[132:133], v[6:7] op_sel_hi:[0,1,1]
	v_pk_fma_f32 v[8:9], v[28:29], v[134:135], v[8:9] op_sel_hi:[0,1,1]
	v_pk_fma_f32 v[10:11], v[28:29], v[136:137], v[10:11] op_sel_hi:[0,1,1]
	v_pk_fma_f32 v[12:13], v[28:29], v[138:139], v[12:13] op_sel_hi:[0,1,1]
	v_pk_fma_f32 v[14:15], v[28:29], v[140:141], v[14:15] op_sel_hi:[0,1,1]
	v_pk_fma_f32 v[16:17], v[28:29], v[142:143], v[16:17] op_sel_hi:[0,1,1]
	v_pk_fma_f32 v[18:19], v[28:29], v[144:145], v[18:19] op_sel_hi:[0,1,1]
	v_fmac_f32_e32 v27, v28, v146
	v_add_u32_e32 v23, 16, v20
	ds_read2st64_b32 v[130:131], v23 offset1:16
	ds_read2st64_b32 v[132:133], v23 offset0:32 offset1:48
	ds_read2st64_b32 v[134:135], v23 offset0:64 offset1:80
	ds_read2st64_b32 v[136:137], v23 offset0:96 offset1:112
	ds_read2st64_b32 v[138:139], v23 offset0:128 offset1:144
	ds_read2st64_b32 v[140:141], v23 offset0:160 offset1:176
	ds_read2st64_b32 v[142:143], v23 offset0:192 offset1:208
	ds_read2st64_b32 v[144:145], v23 offset0:224 offset1:240
	ds_read_b32 v146, v21 offset:16
	s_waitcnt vmcnt(30) lgkmcnt(9)
	v_pk_fma_f32 v[4:5], v[28:29], v[70:71], v[4:5] op_sel:[1,0,0] op_sel_hi:[1,1,1]
	v_pk_fma_f32 v[6:7], v[28:29], v[72:73], v[6:7] op_sel:[1,0,0] op_sel_hi:[1,1,1]
	v_pk_fma_f32 v[8:9], v[28:29], v[74:75], v[8:9] op_sel:[1,0,0] op_sel_hi:[1,1,1]
	v_pk_fma_f32 v[10:11], v[28:29], v[76:77], v[10:11] op_sel:[1,0,0] op_sel_hi:[1,1,1]
	v_pk_fma_f32 v[12:13], v[28:29], v[78:79], v[12:13] op_sel:[1,0,0] op_sel_hi:[1,1,1]
	v_pk_fma_f32 v[14:15], v[28:29], v[80:81], v[14:15] op_sel:[1,0,0] op_sel_hi:[1,1,1]
	v_pk_fma_f32 v[16:17], v[28:29], v[82:83], v[16:17] op_sel:[1,0,0] op_sel_hi:[1,1,1]
	v_pk_fma_f32 v[18:19], v[28:29], v[84:85], v[18:19] op_sel:[1,0,0] op_sel_hi:[1,1,1]
	v_fmac_f32_e32 v27, v29, v86
	v_add_u32_e32 v26, 24, v20
	ds_read2st64_b32 v[70:71], v26 offset1:16
	ds_read2st64_b32 v[72:73], v26 offset0:32 offset1:48
	ds_read2st64_b32 v[74:75], v26 offset0:64 offset1:80
	ds_read2st64_b32 v[76:77], v26 offset0:96 offset1:112
	ds_read2st64_b32 v[78:79], v26 offset0:128 offset1:144
	ds_read2st64_b32 v[80:81], v26 offset0:160 offset1:176
	ds_read2st64_b32 v[82:83], v26 offset0:192 offset1:208
	ds_read2st64_b32 v[84:85], v26 offset0:224 offset1:240
	ds_read_b32 v86, v21 offset:24
	s_waitcnt vmcnt(29) lgkmcnt(9)
	v_pk_fma_f32 v[4:5], v[30:31], v[130:131], v[4:5] op_sel_hi:[0,1,1]
	v_pk_fma_f32 v[6:7], v[30:31], v[132:133], v[6:7] op_sel_hi:[0,1,1]
	v_pk_fma_f32 v[8:9], v[30:31], v[134:135], v[8:9] op_sel_hi:[0,1,1]
	v_pk_fma_f32 v[10:11], v[30:31], v[136:137], v[10:11] op_sel_hi:[0,1,1]
	v_pk_fma_f32 v[12:13], v[30:31], v[138:139], v[12:13] op_sel_hi:[0,1,1]
	v_pk_fma_f32 v[14:15], v[30:31], v[140:141], v[14:15] op_sel_hi:[0,1,1]
	v_pk_fma_f32 v[16:17], v[30:31], v[142:143], v[16:17] op_sel_hi:[0,1,1]
	v_pk_fma_f32 v[18:19], v[30:31], v[144:145], v[18:19] op_sel_hi:[0,1,1]
	v_fmac_f32_e32 v27, v30, v146
	v_add_u32_e32 v23, 32, v20
	ds_read2st64_b32 v[130:131], v23 offset1:16
	ds_read2st64_b32 v[132:133], v23 offset0:32 offset1:48
	ds_read2st64_b32 v[134:135], v23 offset0:64 offset1:80
	ds_read2st64_b32 v[136:137], v23 offset0:96 offset1:112
	ds_read2st64_b32 v[138:139], v23 offset0:128 offset1:144
	ds_read2st64_b32 v[140:141], v23 offset0:160 offset1:176
	ds_read2st64_b32 v[142:143], v23 offset0:192 offset1:208
	ds_read2st64_b32 v[144:145], v23 offset0:224 offset1:240
	ds_read_b32 v146, v21 offset:32
	s_waitcnt vmcnt(28) lgkmcnt(9)
	v_pk_fma_f32 v[4:5], v[30:31], v[70:71], v[4:5] op_sel:[1,0,0] op_sel_hi:[1,1,1]
	v_pk_fma_f32 v[6:7], v[30:31], v[72:73], v[6:7] op_sel:[1,0,0] op_sel_hi:[1,1,1]
	v_pk_fma_f32 v[8:9], v[30:31], v[74:75], v[8:9] op_sel:[1,0,0] op_sel_hi:[1,1,1]
	v_pk_fma_f32 v[10:11], v[30:31], v[76:77], v[10:11] op_sel:[1,0,0] op_sel_hi:[1,1,1]
	v_pk_fma_f32 v[12:13], v[30:31], v[78:79], v[12:13] op_sel:[1,0,0] op_sel_hi:[1,1,1]
	v_pk_fma_f32 v[14:15], v[30:31], v[80:81], v[14:15] op_sel:[1,0,0] op_sel_hi:[1,1,1]
	v_pk_fma_f32 v[16:17], v[30:31], v[82:83], v[16:17] op_sel:[1,0,0] op_sel_hi:[1,1,1]
	v_pk_fma_f32 v[18:19], v[30:31], v[84:85], v[18:19] op_sel:[1,0,0] op_sel_hi:[1,1,1]
	v_fmac_f32_e32 v27, v31, v86
	v_add_u32_e32 v26, 40, v20
	ds_read2st64_b32 v[70:71], v26 offset1:16
	ds_read2st64_b32 v[72:73], v26 offset0:32 offset1:48
	ds_read2st64_b32 v[74:75], v26 offset0:64 offset1:80
	ds_read2st64_b32 v[76:77], v26 offset0:96 offset1:112
	ds_read2st64_b32 v[78:79], v26 offset0:128 offset1:144
	ds_read2st64_b32 v[80:81], v26 offset0:160 offset1:176
	ds_read2st64_b32 v[82:83], v26 offset0:192 offset1:208
	ds_read2st64_b32 v[84:85], v26 offset0:224 offset1:240
	ds_read_b32 v86, v21 offset:40
	s_waitcnt vmcnt(27) lgkmcnt(9)
	v_pk_fma_f32 v[4:5], v[32:33], v[130:131], v[4:5] op_sel_hi:[0,1,1]
	v_pk_fma_f32 v[6:7], v[32:33], v[132:133], v[6:7] op_sel_hi:[0,1,1]
	v_pk_fma_f32 v[8:9], v[32:33], v[134:135], v[8:9] op_sel_hi:[0,1,1]
	v_pk_fma_f32 v[10:11], v[32:33], v[136:137], v[10:11] op_sel_hi:[0,1,1]
	v_pk_fma_f32 v[12:13], v[32:33], v[138:139], v[12:13] op_sel_hi:[0,1,1]
	v_pk_fma_f32 v[14:15], v[32:33], v[140:141], v[14:15] op_sel_hi:[0,1,1]
	v_pk_fma_f32 v[16:17], v[32:33], v[142:143], v[16:17] op_sel_hi:[0,1,1]
	v_pk_fma_f32 v[18:19], v[32:33], v[144:145], v[18:19] op_sel_hi:[0,1,1]
	v_fmac_f32_e32 v27, v32, v146
	v_add_u32_e32 v23, 48, v20
	ds_read2st64_b32 v[130:131], v23 offset1:16
	ds_read2st64_b32 v[132:133], v23 offset0:32 offset1:48
	ds_read2st64_b32 v[134:135], v23 offset0:64 offset1:80
	ds_read2st64_b32 v[136:137], v23 offset0:96 offset1:112
	ds_read2st64_b32 v[138:139], v23 offset0:128 offset1:144
	ds_read2st64_b32 v[140:141], v23 offset0:160 offset1:176
	ds_read2st64_b32 v[142:143], v23 offset0:192 offset1:208
	ds_read2st64_b32 v[144:145], v23 offset0:224 offset1:240
	ds_read_b32 v146, v21 offset:48
	s_waitcnt vmcnt(26) lgkmcnt(9)
	v_pk_fma_f32 v[4:5], v[32:33], v[70:71], v[4:5] op_sel:[1,0,0] op_sel_hi:[1,1,1]
	v_pk_fma_f32 v[6:7], v[32:33], v[72:73], v[6:7] op_sel:[1,0,0] op_sel_hi:[1,1,1]
	v_pk_fma_f32 v[8:9], v[32:33], v[74:75], v[8:9] op_sel:[1,0,0] op_sel_hi:[1,1,1]
	v_pk_fma_f32 v[10:11], v[32:33], v[76:77], v[10:11] op_sel:[1,0,0] op_sel_hi:[1,1,1]
	v_pk_fma_f32 v[12:13], v[32:33], v[78:79], v[12:13] op_sel:[1,0,0] op_sel_hi:[1,1,1]
	v_pk_fma_f32 v[14:15], v[32:33], v[80:81], v[14:15] op_sel:[1,0,0] op_sel_hi:[1,1,1]
	v_pk_fma_f32 v[16:17], v[32:33], v[82:83], v[16:17] op_sel:[1,0,0] op_sel_hi:[1,1,1]
	v_pk_fma_f32 v[18:19], v[32:33], v[84:85], v[18:19] op_sel:[1,0,0] op_sel_hi:[1,1,1]
	v_fmac_f32_e32 v27, v33, v86
	v_add_u32_e32 v26, 56, v20
	ds_read2st64_b32 v[70:71], v26 offset1:16
	ds_read2st64_b32 v[72:73], v26 offset0:32 offset1:48
	ds_read2st64_b32 v[74:75], v26 offset0:64 offset1:80
	ds_read2st64_b32 v[76:77], v26 offset0:96 offset1:112
	ds_read2st64_b32 v[78:79], v26 offset0:128 offset1:144
	ds_read2st64_b32 v[80:81], v26 offset0:160 offset1:176
	ds_read2st64_b32 v[82:83], v26 offset0:192 offset1:208
	ds_read2st64_b32 v[84:85], v26 offset0:224 offset1:240
	ds_read_b32 v86, v21 offset:56
	s_waitcnt vmcnt(25) lgkmcnt(9)
	v_pk_fma_f32 v[4:5], v[34:35], v[130:131], v[4:5] op_sel_hi:[0,1,1]
	v_pk_fma_f32 v[6:7], v[34:35], v[132:133], v[6:7] op_sel_hi:[0,1,1]
	v_pk_fma_f32 v[8:9], v[34:35], v[134:135], v[8:9] op_sel_hi:[0,1,1]
	v_pk_fma_f32 v[10:11], v[34:35], v[136:137], v[10:11] op_sel_hi:[0,1,1]
	v_pk_fma_f32 v[12:13], v[34:35], v[138:139], v[12:13] op_sel_hi:[0,1,1]
	v_pk_fma_f32 v[14:15], v[34:35], v[140:141], v[14:15] op_sel_hi:[0,1,1]
	v_pk_fma_f32 v[16:17], v[34:35], v[142:143], v[16:17] op_sel_hi:[0,1,1]
	v_pk_fma_f32 v[18:19], v[34:35], v[144:145], v[18:19] op_sel_hi:[0,1,1]
	v_fmac_f32_e32 v27, v34, v146
	v_add_u32_e32 v23, 64, v20
	ds_read2st64_b32 v[130:131], v23 offset1:16
	ds_read2st64_b32 v[132:133], v23 offset0:32 offset1:48
	ds_read2st64_b32 v[134:135], v23 offset0:64 offset1:80
	ds_read2st64_b32 v[136:137], v23 offset0:96 offset1:112
	ds_read2st64_b32 v[138:139], v23 offset0:128 offset1:144
	ds_read2st64_b32 v[140:141], v23 offset0:160 offset1:176
	ds_read2st64_b32 v[142:143], v23 offset0:192 offset1:208
	ds_read2st64_b32 v[144:145], v23 offset0:224 offset1:240
	ds_read_b32 v146, v21 offset:64
	s_waitcnt vmcnt(24) lgkmcnt(9)
	v_pk_fma_f32 v[4:5], v[34:35], v[70:71], v[4:5] op_sel:[1,0,0] op_sel_hi:[1,1,1]
	v_pk_fma_f32 v[6:7], v[34:35], v[72:73], v[6:7] op_sel:[1,0,0] op_sel_hi:[1,1,1]
	v_pk_fma_f32 v[8:9], v[34:35], v[74:75], v[8:9] op_sel:[1,0,0] op_sel_hi:[1,1,1]
	v_pk_fma_f32 v[10:11], v[34:35], v[76:77], v[10:11] op_sel:[1,0,0] op_sel_hi:[1,1,1]
	v_pk_fma_f32 v[12:13], v[34:35], v[78:79], v[12:13] op_sel:[1,0,0] op_sel_hi:[1,1,1]
	v_pk_fma_f32 v[14:15], v[34:35], v[80:81], v[14:15] op_sel:[1,0,0] op_sel_hi:[1,1,1]
	v_pk_fma_f32 v[16:17], v[34:35], v[82:83], v[16:17] op_sel:[1,0,0] op_sel_hi:[1,1,1]
	v_pk_fma_f32 v[18:19], v[34:35], v[84:85], v[18:19] op_sel:[1,0,0] op_sel_hi:[1,1,1]
	v_fmac_f32_e32 v27, v35, v86
	v_add_u32_e32 v26, 72, v20
	ds_read2st64_b32 v[70:71], v26 offset1:16
	ds_read2st64_b32 v[72:73], v26 offset0:32 offset1:48
	ds_read2st64_b32 v[74:75], v26 offset0:64 offset1:80
	ds_read2st64_b32 v[76:77], v26 offset0:96 offset1:112
	ds_read2st64_b32 v[78:79], v26 offset0:128 offset1:144
	ds_read2st64_b32 v[80:81], v26 offset0:160 offset1:176
	ds_read2st64_b32 v[82:83], v26 offset0:192 offset1:208
	ds_read2st64_b32 v[84:85], v26 offset0:224 offset1:240
	ds_read_b32 v86, v21 offset:72
	s_waitcnt vmcnt(23) lgkmcnt(9)
	v_pk_fma_f32 v[4:5], v[36:37], v[130:131], v[4:5] op_sel_hi:[0,1,1]
	v_pk_fma_f32 v[6:7], v[36:37], v[132:133], v[6:7] op_sel_hi:[0,1,1]
	v_pk_fma_f32 v[8:9], v[36:37], v[134:135], v[8:9] op_sel_hi:[0,1,1]
	v_pk_fma_f32 v[10:11], v[36:37], v[136:137], v[10:11] op_sel_hi:[0,1,1]
	v_pk_fma_f32 v[12:13], v[36:37], v[138:139], v[12:13] op_sel_hi:[0,1,1]
	v_pk_fma_f32 v[14:15], v[36:37], v[140:141], v[14:15] op_sel_hi:[0,1,1]
	v_pk_fma_f32 v[16:17], v[36:37], v[142:143], v[16:17] op_sel_hi:[0,1,1]
	v_pk_fma_f32 v[18:19], v[36:37], v[144:145], v[18:19] op_sel_hi:[0,1,1]
	v_fmac_f32_e32 v27, v36, v146
	v_add_u32_e32 v23, 80, v20
	ds_read2st64_b32 v[130:131], v23 offset1:16
	ds_read2st64_b32 v[132:133], v23 offset0:32 offset1:48
	ds_read2st64_b32 v[134:135], v23 offset0:64 offset1:80
	ds_read2st64_b32 v[136:137], v23 offset0:96 offset1:112
	ds_read2st64_b32 v[138:139], v23 offset0:128 offset1:144
	ds_read2st64_b32 v[140:141], v23 offset0:160 offset1:176
	ds_read2st64_b32 v[142:143], v23 offset0:192 offset1:208
	ds_read2st64_b32 v[144:145], v23 offset0:224 offset1:240
	ds_read_b32 v146, v21 offset:80
	s_waitcnt vmcnt(22) lgkmcnt(9)
	v_pk_fma_f32 v[4:5], v[36:37], v[70:71], v[4:5] op_sel:[1,0,0] op_sel_hi:[1,1,1]
	v_pk_fma_f32 v[6:7], v[36:37], v[72:73], v[6:7] op_sel:[1,0,0] op_sel_hi:[1,1,1]
	v_pk_fma_f32 v[8:9], v[36:37], v[74:75], v[8:9] op_sel:[1,0,0] op_sel_hi:[1,1,1]
	v_pk_fma_f32 v[10:11], v[36:37], v[76:77], v[10:11] op_sel:[1,0,0] op_sel_hi:[1,1,1]
	v_pk_fma_f32 v[12:13], v[36:37], v[78:79], v[12:13] op_sel:[1,0,0] op_sel_hi:[1,1,1]
	v_pk_fma_f32 v[14:15], v[36:37], v[80:81], v[14:15] op_sel:[1,0,0] op_sel_hi:[1,1,1]
	v_pk_fma_f32 v[16:17], v[36:37], v[82:83], v[16:17] op_sel:[1,0,0] op_sel_hi:[1,1,1]
	v_pk_fma_f32 v[18:19], v[36:37], v[84:85], v[18:19] op_sel:[1,0,0] op_sel_hi:[1,1,1]
	v_fmac_f32_e32 v27, v37, v86
	v_add_u32_e32 v26, 88, v20
	ds_read2st64_b32 v[70:71], v26 offset1:16
	ds_read2st64_b32 v[72:73], v26 offset0:32 offset1:48
	ds_read2st64_b32 v[74:75], v26 offset0:64 offset1:80
	ds_read2st64_b32 v[76:77], v26 offset0:96 offset1:112
	ds_read2st64_b32 v[78:79], v26 offset0:128 offset1:144
	ds_read2st64_b32 v[80:81], v26 offset0:160 offset1:176
	ds_read2st64_b32 v[82:83], v26 offset0:192 offset1:208
	ds_read2st64_b32 v[84:85], v26 offset0:224 offset1:240
	ds_read_b32 v86, v21 offset:88
	s_waitcnt vmcnt(21) lgkmcnt(9)
	v_pk_fma_f32 v[4:5], v[38:39], v[130:131], v[4:5] op_sel_hi:[0,1,1]
	v_pk_fma_f32 v[6:7], v[38:39], v[132:133], v[6:7] op_sel_hi:[0,1,1]
	v_pk_fma_f32 v[8:9], v[38:39], v[134:135], v[8:9] op_sel_hi:[0,1,1]
	v_pk_fma_f32 v[10:11], v[38:39], v[136:137], v[10:11] op_sel_hi:[0,1,1]
	v_pk_fma_f32 v[12:13], v[38:39], v[138:139], v[12:13] op_sel_hi:[0,1,1]
	v_pk_fma_f32 v[14:15], v[38:39], v[140:141], v[14:15] op_sel_hi:[0,1,1]
	v_pk_fma_f32 v[16:17], v[38:39], v[142:143], v[16:17] op_sel_hi:[0,1,1]
	v_pk_fma_f32 v[18:19], v[38:39], v[144:145], v[18:19] op_sel_hi:[0,1,1]
	v_fmac_f32_e32 v27, v38, v146
	v_add_u32_e32 v23, 96, v20
	ds_read2st64_b32 v[130:131], v23 offset1:16
	ds_read2st64_b32 v[132:133], v23 offset0:32 offset1:48
	ds_read2st64_b32 v[134:135], v23 offset0:64 offset1:80
	ds_read2st64_b32 v[136:137], v23 offset0:96 offset1:112
	ds_read2st64_b32 v[138:139], v23 offset0:128 offset1:144
	ds_read2st64_b32 v[140:141], v23 offset0:160 offset1:176
	ds_read2st64_b32 v[142:143], v23 offset0:192 offset1:208
	ds_read2st64_b32 v[144:145], v23 offset0:224 offset1:240
	ds_read_b32 v146, v21 offset:96
	s_waitcnt vmcnt(20) lgkmcnt(9)
	v_pk_fma_f32 v[4:5], v[38:39], v[70:71], v[4:5] op_sel:[1,0,0] op_sel_hi:[1,1,1]
	v_pk_fma_f32 v[6:7], v[38:39], v[72:73], v[6:7] op_sel:[1,0,0] op_sel_hi:[1,1,1]
	v_pk_fma_f32 v[8:9], v[38:39], v[74:75], v[8:9] op_sel:[1,0,0] op_sel_hi:[1,1,1]
	v_pk_fma_f32 v[10:11], v[38:39], v[76:77], v[10:11] op_sel:[1,0,0] op_sel_hi:[1,1,1]
	v_pk_fma_f32 v[12:13], v[38:39], v[78:79], v[12:13] op_sel:[1,0,0] op_sel_hi:[1,1,1]
	v_pk_fma_f32 v[14:15], v[38:39], v[80:81], v[14:15] op_sel:[1,0,0] op_sel_hi:[1,1,1]
	v_pk_fma_f32 v[16:17], v[38:39], v[82:83], v[16:17] op_sel:[1,0,0] op_sel_hi:[1,1,1]
	v_pk_fma_f32 v[18:19], v[38:39], v[84:85], v[18:19] op_sel:[1,0,0] op_sel_hi:[1,1,1]
	v_fmac_f32_e32 v27, v39, v86
	v_add_u32_e32 v26, 104, v20
	ds_read2st64_b32 v[70:71], v26 offset1:16
	ds_read2st64_b32 v[72:73], v26 offset0:32 offset1:48
	ds_read2st64_b32 v[74:75], v26 offset0:64 offset1:80
	ds_read2st64_b32 v[76:77], v26 offset0:96 offset1:112
	ds_read2st64_b32 v[78:79], v26 offset0:128 offset1:144
	ds_read2st64_b32 v[80:81], v26 offset0:160 offset1:176
	ds_read2st64_b32 v[82:83], v26 offset0:192 offset1:208
	ds_read2st64_b32 v[84:85], v26 offset0:224 offset1:240
	ds_read_b32 v86, v21 offset:104
	s_waitcnt vmcnt(19) lgkmcnt(9)
	v_pk_fma_f32 v[4:5], v[40:41], v[130:131], v[4:5] op_sel_hi:[0,1,1]
	v_pk_fma_f32 v[6:7], v[40:41], v[132:133], v[6:7] op_sel_hi:[0,1,1]
	v_pk_fma_f32 v[8:9], v[40:41], v[134:135], v[8:9] op_sel_hi:[0,1,1]
	v_pk_fma_f32 v[10:11], v[40:41], v[136:137], v[10:11] op_sel_hi:[0,1,1]
	v_pk_fma_f32 v[12:13], v[40:41], v[138:139], v[12:13] op_sel_hi:[0,1,1]
	v_pk_fma_f32 v[14:15], v[40:41], v[140:141], v[14:15] op_sel_hi:[0,1,1]
	v_pk_fma_f32 v[16:17], v[40:41], v[142:143], v[16:17] op_sel_hi:[0,1,1]
	v_pk_fma_f32 v[18:19], v[40:41], v[144:145], v[18:19] op_sel_hi:[0,1,1]
	v_fmac_f32_e32 v27, v40, v146
	v_add_u32_e32 v23, 112, v20
	ds_read2st64_b32 v[130:131], v23 offset1:16
	ds_read2st64_b32 v[132:133], v23 offset0:32 offset1:48
	ds_read2st64_b32 v[134:135], v23 offset0:64 offset1:80
	ds_read2st64_b32 v[136:137], v23 offset0:96 offset1:112
	ds_read2st64_b32 v[138:139], v23 offset0:128 offset1:144
	ds_read2st64_b32 v[140:141], v23 offset0:160 offset1:176
	ds_read2st64_b32 v[142:143], v23 offset0:192 offset1:208
	ds_read2st64_b32 v[144:145], v23 offset0:224 offset1:240
	ds_read_b32 v146, v21 offset:112
	s_waitcnt vmcnt(18) lgkmcnt(9)
	v_pk_fma_f32 v[4:5], v[40:41], v[70:71], v[4:5] op_sel:[1,0,0] op_sel_hi:[1,1,1]
	v_pk_fma_f32 v[6:7], v[40:41], v[72:73], v[6:7] op_sel:[1,0,0] op_sel_hi:[1,1,1]
	v_pk_fma_f32 v[8:9], v[40:41], v[74:75], v[8:9] op_sel:[1,0,0] op_sel_hi:[1,1,1]
	v_pk_fma_f32 v[10:11], v[40:41], v[76:77], v[10:11] op_sel:[1,0,0] op_sel_hi:[1,1,1]
	v_pk_fma_f32 v[12:13], v[40:41], v[78:79], v[12:13] op_sel:[1,0,0] op_sel_hi:[1,1,1]
	v_pk_fma_f32 v[14:15], v[40:41], v[80:81], v[14:15] op_sel:[1,0,0] op_sel_hi:[1,1,1]
	v_pk_fma_f32 v[16:17], v[40:41], v[82:83], v[16:17] op_sel:[1,0,0] op_sel_hi:[1,1,1]
	v_pk_fma_f32 v[18:19], v[40:41], v[84:85], v[18:19] op_sel:[1,0,0] op_sel_hi:[1,1,1]
	v_fmac_f32_e32 v27, v41, v86
	v_add_u32_e32 v26, 120, v20
	ds_read2st64_b32 v[70:71], v26 offset1:16
	ds_read2st64_b32 v[72:73], v26 offset0:32 offset1:48
	ds_read2st64_b32 v[74:75], v26 offset0:64 offset1:80
	ds_read2st64_b32 v[76:77], v26 offset0:96 offset1:112
	ds_read2st64_b32 v[78:79], v26 offset0:128 offset1:144
	ds_read2st64_b32 v[80:81], v26 offset0:160 offset1:176
	ds_read2st64_b32 v[82:83], v26 offset0:192 offset1:208
	ds_read2st64_b32 v[84:85], v26 offset0:224 offset1:240
	ds_read_b32 v86, v21 offset:120
	s_waitcnt vmcnt(17) lgkmcnt(9)
	v_pk_fma_f32 v[4:5], v[42:43], v[130:131], v[4:5] op_sel_hi:[0,1,1]
	v_pk_fma_f32 v[6:7], v[42:43], v[132:133], v[6:7] op_sel_hi:[0,1,1]
	v_pk_fma_f32 v[8:9], v[42:43], v[134:135], v[8:9] op_sel_hi:[0,1,1]
	v_pk_fma_f32 v[10:11], v[42:43], v[136:137], v[10:11] op_sel_hi:[0,1,1]
	v_pk_fma_f32 v[12:13], v[42:43], v[138:139], v[12:13] op_sel_hi:[0,1,1]
	v_pk_fma_f32 v[14:15], v[42:43], v[140:141], v[14:15] op_sel_hi:[0,1,1]
	v_pk_fma_f32 v[16:17], v[42:43], v[142:143], v[16:17] op_sel_hi:[0,1,1]
	v_pk_fma_f32 v[18:19], v[42:43], v[144:145], v[18:19] op_sel_hi:[0,1,1]
	v_fmac_f32_e32 v27, v42, v146
	v_add_u32_e32 v23, 128, v20
	ds_read2st64_b32 v[130:131], v23 offset1:16
	ds_read2st64_b32 v[132:133], v23 offset0:32 offset1:48
	ds_read2st64_b32 v[134:135], v23 offset0:64 offset1:80
	ds_read2st64_b32 v[136:137], v23 offset0:96 offset1:112
	ds_read2st64_b32 v[138:139], v23 offset0:128 offset1:144
	ds_read2st64_b32 v[140:141], v23 offset0:160 offset1:176
	ds_read2st64_b32 v[142:143], v23 offset0:192 offset1:208
	ds_read2st64_b32 v[144:145], v23 offset0:224 offset1:240
	ds_read_b32 v146, v21 offset:128
	s_waitcnt vmcnt(16) lgkmcnt(9)
	v_pk_fma_f32 v[4:5], v[42:43], v[70:71], v[4:5] op_sel:[1,0,0] op_sel_hi:[1,1,1]
	v_pk_fma_f32 v[6:7], v[42:43], v[72:73], v[6:7] op_sel:[1,0,0] op_sel_hi:[1,1,1]
	v_pk_fma_f32 v[8:9], v[42:43], v[74:75], v[8:9] op_sel:[1,0,0] op_sel_hi:[1,1,1]
	v_pk_fma_f32 v[10:11], v[42:43], v[76:77], v[10:11] op_sel:[1,0,0] op_sel_hi:[1,1,1]
	v_pk_fma_f32 v[12:13], v[42:43], v[78:79], v[12:13] op_sel:[1,0,0] op_sel_hi:[1,1,1]
	v_pk_fma_f32 v[14:15], v[42:43], v[80:81], v[14:15] op_sel:[1,0,0] op_sel_hi:[1,1,1]
	v_pk_fma_f32 v[16:17], v[42:43], v[82:83], v[16:17] op_sel:[1,0,0] op_sel_hi:[1,1,1]
	v_pk_fma_f32 v[18:19], v[42:43], v[84:85], v[18:19] op_sel:[1,0,0] op_sel_hi:[1,1,1]
	v_fmac_f32_e32 v27, v43, v86
	v_add_u32_e32 v26, 136, v20
	ds_read2st64_b32 v[70:71], v26 offset1:16
	ds_read2st64_b32 v[72:73], v26 offset0:32 offset1:48
	ds_read2st64_b32 v[74:75], v26 offset0:64 offset1:80
	ds_read2st64_b32 v[76:77], v26 offset0:96 offset1:112
	ds_read2st64_b32 v[78:79], v26 offset0:128 offset1:144
	ds_read2st64_b32 v[80:81], v26 offset0:160 offset1:176
	ds_read2st64_b32 v[82:83], v26 offset0:192 offset1:208
	ds_read2st64_b32 v[84:85], v26 offset0:224 offset1:240
	ds_read_b32 v86, v21 offset:136
	s_waitcnt vmcnt(15) lgkmcnt(9)
	v_pk_fma_f32 v[4:5], v[44:45], v[130:131], v[4:5] op_sel_hi:[0,1,1]
	v_pk_fma_f32 v[6:7], v[44:45], v[132:133], v[6:7] op_sel_hi:[0,1,1]
	v_pk_fma_f32 v[8:9], v[44:45], v[134:135], v[8:9] op_sel_hi:[0,1,1]
	v_pk_fma_f32 v[10:11], v[44:45], v[136:137], v[10:11] op_sel_hi:[0,1,1]
	v_pk_fma_f32 v[12:13], v[44:45], v[138:139], v[12:13] op_sel_hi:[0,1,1]
	v_pk_fma_f32 v[14:15], v[44:45], v[140:141], v[14:15] op_sel_hi:[0,1,1]
	v_pk_fma_f32 v[16:17], v[44:45], v[142:143], v[16:17] op_sel_hi:[0,1,1]
	v_pk_fma_f32 v[18:19], v[44:45], v[144:145], v[18:19] op_sel_hi:[0,1,1]
	v_fmac_f32_e32 v27, v44, v146
	v_add_u32_e32 v23, 144, v20
	ds_read2st64_b32 v[130:131], v23 offset1:16
	ds_read2st64_b32 v[132:133], v23 offset0:32 offset1:48
	ds_read2st64_b32 v[134:135], v23 offset0:64 offset1:80
	ds_read2st64_b32 v[136:137], v23 offset0:96 offset1:112
	ds_read2st64_b32 v[138:139], v23 offset0:128 offset1:144
	ds_read2st64_b32 v[140:141], v23 offset0:160 offset1:176
	ds_read2st64_b32 v[142:143], v23 offset0:192 offset1:208
	ds_read2st64_b32 v[144:145], v23 offset0:224 offset1:240
	ds_read_b32 v146, v21 offset:144
	s_waitcnt vmcnt(14) lgkmcnt(9)
	v_pk_fma_f32 v[4:5], v[44:45], v[70:71], v[4:5] op_sel:[1,0,0] op_sel_hi:[1,1,1]
	v_pk_fma_f32 v[6:7], v[44:45], v[72:73], v[6:7] op_sel:[1,0,0] op_sel_hi:[1,1,1]
	v_pk_fma_f32 v[8:9], v[44:45], v[74:75], v[8:9] op_sel:[1,0,0] op_sel_hi:[1,1,1]
	v_pk_fma_f32 v[10:11], v[44:45], v[76:77], v[10:11] op_sel:[1,0,0] op_sel_hi:[1,1,1]
	v_pk_fma_f32 v[12:13], v[44:45], v[78:79], v[12:13] op_sel:[1,0,0] op_sel_hi:[1,1,1]
	v_pk_fma_f32 v[14:15], v[44:45], v[80:81], v[14:15] op_sel:[1,0,0] op_sel_hi:[1,1,1]
	v_pk_fma_f32 v[16:17], v[44:45], v[82:83], v[16:17] op_sel:[1,0,0] op_sel_hi:[1,1,1]
	v_pk_fma_f32 v[18:19], v[44:45], v[84:85], v[18:19] op_sel:[1,0,0] op_sel_hi:[1,1,1]
	v_fmac_f32_e32 v27, v45, v86
	v_add_u32_e32 v26, 152, v20
	ds_read2st64_b32 v[70:71], v26 offset1:16
	ds_read2st64_b32 v[72:73], v26 offset0:32 offset1:48
	ds_read2st64_b32 v[74:75], v26 offset0:64 offset1:80
	ds_read2st64_b32 v[76:77], v26 offset0:96 offset1:112
	ds_read2st64_b32 v[78:79], v26 offset0:128 offset1:144
	ds_read2st64_b32 v[80:81], v26 offset0:160 offset1:176
	ds_read2st64_b32 v[82:83], v26 offset0:192 offset1:208
	ds_read2st64_b32 v[84:85], v26 offset0:224 offset1:240
	ds_read_b32 v86, v21 offset:152
	s_waitcnt vmcnt(13) lgkmcnt(9)
	v_pk_fma_f32 v[4:5], v[46:47], v[130:131], v[4:5] op_sel_hi:[0,1,1]
	v_pk_fma_f32 v[6:7], v[46:47], v[132:133], v[6:7] op_sel_hi:[0,1,1]
	v_pk_fma_f32 v[8:9], v[46:47], v[134:135], v[8:9] op_sel_hi:[0,1,1]
	v_pk_fma_f32 v[10:11], v[46:47], v[136:137], v[10:11] op_sel_hi:[0,1,1]
	v_pk_fma_f32 v[12:13], v[46:47], v[138:139], v[12:13] op_sel_hi:[0,1,1]
	v_pk_fma_f32 v[14:15], v[46:47], v[140:141], v[14:15] op_sel_hi:[0,1,1]
	v_pk_fma_f32 v[16:17], v[46:47], v[142:143], v[16:17] op_sel_hi:[0,1,1]
	v_pk_fma_f32 v[18:19], v[46:47], v[144:145], v[18:19] op_sel_hi:[0,1,1]
	v_fmac_f32_e32 v27, v46, v146
	v_add_u32_e32 v23, 160, v20
	ds_read2st64_b32 v[130:131], v23 offset1:16
	ds_read2st64_b32 v[132:133], v23 offset0:32 offset1:48
	ds_read2st64_b32 v[134:135], v23 offset0:64 offset1:80
	ds_read2st64_b32 v[136:137], v23 offset0:96 offset1:112
	ds_read2st64_b32 v[138:139], v23 offset0:128 offset1:144
	ds_read2st64_b32 v[140:141], v23 offset0:160 offset1:176
	ds_read2st64_b32 v[142:143], v23 offset0:192 offset1:208
	ds_read2st64_b32 v[144:145], v23 offset0:224 offset1:240
	ds_read_b32 v146, v21 offset:160
	s_waitcnt vmcnt(12) lgkmcnt(9)
	v_pk_fma_f32 v[4:5], v[46:47], v[70:71], v[4:5] op_sel:[1,0,0] op_sel_hi:[1,1,1]
	v_pk_fma_f32 v[6:7], v[46:47], v[72:73], v[6:7] op_sel:[1,0,0] op_sel_hi:[1,1,1]
	v_pk_fma_f32 v[8:9], v[46:47], v[74:75], v[8:9] op_sel:[1,0,0] op_sel_hi:[1,1,1]
	v_pk_fma_f32 v[10:11], v[46:47], v[76:77], v[10:11] op_sel:[1,0,0] op_sel_hi:[1,1,1]
	v_pk_fma_f32 v[12:13], v[46:47], v[78:79], v[12:13] op_sel:[1,0,0] op_sel_hi:[1,1,1]
	v_pk_fma_f32 v[14:15], v[46:47], v[80:81], v[14:15] op_sel:[1,0,0] op_sel_hi:[1,1,1]
	v_pk_fma_f32 v[16:17], v[46:47], v[82:83], v[16:17] op_sel:[1,0,0] op_sel_hi:[1,1,1]
	v_pk_fma_f32 v[18:19], v[46:47], v[84:85], v[18:19] op_sel:[1,0,0] op_sel_hi:[1,1,1]
	v_fmac_f32_e32 v27, v47, v86
	v_add_u32_e32 v26, 168, v20
	ds_read2st64_b32 v[70:71], v26 offset1:16
	ds_read2st64_b32 v[72:73], v26 offset0:32 offset1:48
	ds_read2st64_b32 v[74:75], v26 offset0:64 offset1:80
	ds_read2st64_b32 v[76:77], v26 offset0:96 offset1:112
	ds_read2st64_b32 v[78:79], v26 offset0:128 offset1:144
	ds_read2st64_b32 v[80:81], v26 offset0:160 offset1:176
	ds_read2st64_b32 v[82:83], v26 offset0:192 offset1:208
	ds_read2st64_b32 v[84:85], v26 offset0:224 offset1:240
	ds_read_b32 v86, v21 offset:168
	s_waitcnt vmcnt(11) lgkmcnt(9)
	v_pk_fma_f32 v[4:5], v[48:49], v[130:131], v[4:5] op_sel_hi:[0,1,1]
	v_pk_fma_f32 v[6:7], v[48:49], v[132:133], v[6:7] op_sel_hi:[0,1,1]
	v_pk_fma_f32 v[8:9], v[48:49], v[134:135], v[8:9] op_sel_hi:[0,1,1]
	v_pk_fma_f32 v[10:11], v[48:49], v[136:137], v[10:11] op_sel_hi:[0,1,1]
	v_pk_fma_f32 v[12:13], v[48:49], v[138:139], v[12:13] op_sel_hi:[0,1,1]
	v_pk_fma_f32 v[14:15], v[48:49], v[140:141], v[14:15] op_sel_hi:[0,1,1]
	v_pk_fma_f32 v[16:17], v[48:49], v[142:143], v[16:17] op_sel_hi:[0,1,1]
	v_pk_fma_f32 v[18:19], v[48:49], v[144:145], v[18:19] op_sel_hi:[0,1,1]
	v_fmac_f32_e32 v27, v48, v146
	v_add_u32_e32 v23, 176, v20
	ds_read2st64_b32 v[130:131], v23 offset1:16
	ds_read2st64_b32 v[132:133], v23 offset0:32 offset1:48
	ds_read2st64_b32 v[134:135], v23 offset0:64 offset1:80
	ds_read2st64_b32 v[136:137], v23 offset0:96 offset1:112
	ds_read2st64_b32 v[138:139], v23 offset0:128 offset1:144
	ds_read2st64_b32 v[140:141], v23 offset0:160 offset1:176
	ds_read2st64_b32 v[142:143], v23 offset0:192 offset1:208
	ds_read2st64_b32 v[144:145], v23 offset0:224 offset1:240
	ds_read_b32 v146, v21 offset:176
	s_waitcnt vmcnt(10) lgkmcnt(9)
	v_pk_fma_f32 v[4:5], v[48:49], v[70:71], v[4:5] op_sel:[1,0,0] op_sel_hi:[1,1,1]
	v_pk_fma_f32 v[6:7], v[48:49], v[72:73], v[6:7] op_sel:[1,0,0] op_sel_hi:[1,1,1]
	v_pk_fma_f32 v[8:9], v[48:49], v[74:75], v[8:9] op_sel:[1,0,0] op_sel_hi:[1,1,1]
	v_pk_fma_f32 v[10:11], v[48:49], v[76:77], v[10:11] op_sel:[1,0,0] op_sel_hi:[1,1,1]
	v_pk_fma_f32 v[12:13], v[48:49], v[78:79], v[12:13] op_sel:[1,0,0] op_sel_hi:[1,1,1]
	v_pk_fma_f32 v[14:15], v[48:49], v[80:81], v[14:15] op_sel:[1,0,0] op_sel_hi:[1,1,1]
	v_pk_fma_f32 v[16:17], v[48:49], v[82:83], v[16:17] op_sel:[1,0,0] op_sel_hi:[1,1,1]
	v_pk_fma_f32 v[18:19], v[48:49], v[84:85], v[18:19] op_sel:[1,0,0] op_sel_hi:[1,1,1]
	v_fmac_f32_e32 v27, v49, v86
	v_add_u32_e32 v26, 184, v20
	ds_read2st64_b32 v[70:71], v26 offset1:16
	ds_read2st64_b32 v[72:73], v26 offset0:32 offset1:48
	ds_read2st64_b32 v[74:75], v26 offset0:64 offset1:80
	ds_read2st64_b32 v[76:77], v26 offset0:96 offset1:112
	ds_read2st64_b32 v[78:79], v26 offset0:128 offset1:144
	ds_read2st64_b32 v[80:81], v26 offset0:160 offset1:176
	ds_read2st64_b32 v[82:83], v26 offset0:192 offset1:208
	ds_read2st64_b32 v[84:85], v26 offset0:224 offset1:240
	ds_read_b32 v86, v21 offset:184
	s_waitcnt vmcnt(9) lgkmcnt(9)
	v_pk_fma_f32 v[4:5], v[50:51], v[130:131], v[4:5] op_sel_hi:[0,1,1]
	v_pk_fma_f32 v[6:7], v[50:51], v[132:133], v[6:7] op_sel_hi:[0,1,1]
	v_pk_fma_f32 v[8:9], v[50:51], v[134:135], v[8:9] op_sel_hi:[0,1,1]
	v_pk_fma_f32 v[10:11], v[50:51], v[136:137], v[10:11] op_sel_hi:[0,1,1]
	v_pk_fma_f32 v[12:13], v[50:51], v[138:139], v[12:13] op_sel_hi:[0,1,1]
	v_pk_fma_f32 v[14:15], v[50:51], v[140:141], v[14:15] op_sel_hi:[0,1,1]
	v_pk_fma_f32 v[16:17], v[50:51], v[142:143], v[16:17] op_sel_hi:[0,1,1]
	v_pk_fma_f32 v[18:19], v[50:51], v[144:145], v[18:19] op_sel_hi:[0,1,1]
	v_fmac_f32_e32 v27, v50, v146
	v_add_u32_e32 v23, 192, v20
	ds_read2st64_b32 v[130:131], v23 offset1:16
	ds_read2st64_b32 v[132:133], v23 offset0:32 offset1:48
	ds_read2st64_b32 v[134:135], v23 offset0:64 offset1:80
	ds_read2st64_b32 v[136:137], v23 offset0:96 offset1:112
	ds_read2st64_b32 v[138:139], v23 offset0:128 offset1:144
	ds_read2st64_b32 v[140:141], v23 offset0:160 offset1:176
	ds_read2st64_b32 v[142:143], v23 offset0:192 offset1:208
	ds_read2st64_b32 v[144:145], v23 offset0:224 offset1:240
	ds_read_b32 v146, v21 offset:192
	s_waitcnt vmcnt(8) lgkmcnt(9)
	v_pk_fma_f32 v[4:5], v[50:51], v[70:71], v[4:5] op_sel:[1,0,0] op_sel_hi:[1,1,1]
	v_pk_fma_f32 v[6:7], v[50:51], v[72:73], v[6:7] op_sel:[1,0,0] op_sel_hi:[1,1,1]
	v_pk_fma_f32 v[8:9], v[50:51], v[74:75], v[8:9] op_sel:[1,0,0] op_sel_hi:[1,1,1]
	v_pk_fma_f32 v[10:11], v[50:51], v[76:77], v[10:11] op_sel:[1,0,0] op_sel_hi:[1,1,1]
	v_pk_fma_f32 v[12:13], v[50:51], v[78:79], v[12:13] op_sel:[1,0,0] op_sel_hi:[1,1,1]
	v_pk_fma_f32 v[14:15], v[50:51], v[80:81], v[14:15] op_sel:[1,0,0] op_sel_hi:[1,1,1]
	v_pk_fma_f32 v[16:17], v[50:51], v[82:83], v[16:17] op_sel:[1,0,0] op_sel_hi:[1,1,1]
	v_pk_fma_f32 v[18:19], v[50:51], v[84:85], v[18:19] op_sel:[1,0,0] op_sel_hi:[1,1,1]
	v_fmac_f32_e32 v27, v51, v86
	v_add_u32_e32 v26, 200, v20
	ds_read2st64_b32 v[70:71], v26 offset1:16
	ds_read2st64_b32 v[72:73], v26 offset0:32 offset1:48
	ds_read2st64_b32 v[74:75], v26 offset0:64 offset1:80
	ds_read2st64_b32 v[76:77], v26 offset0:96 offset1:112
	ds_read2st64_b32 v[78:79], v26 offset0:128 offset1:144
	ds_read2st64_b32 v[80:81], v26 offset0:160 offset1:176
	ds_read2st64_b32 v[82:83], v26 offset0:192 offset1:208
	ds_read2st64_b32 v[84:85], v26 offset0:224 offset1:240
	ds_read_b32 v86, v21 offset:200
	s_waitcnt vmcnt(7) lgkmcnt(9)
	v_pk_fma_f32 v[4:5], v[52:53], v[130:131], v[4:5] op_sel_hi:[0,1,1]
	v_pk_fma_f32 v[6:7], v[52:53], v[132:133], v[6:7] op_sel_hi:[0,1,1]
	v_pk_fma_f32 v[8:9], v[52:53], v[134:135], v[8:9] op_sel_hi:[0,1,1]
	v_pk_fma_f32 v[10:11], v[52:53], v[136:137], v[10:11] op_sel_hi:[0,1,1]
	v_pk_fma_f32 v[12:13], v[52:53], v[138:139], v[12:13] op_sel_hi:[0,1,1]
	v_pk_fma_f32 v[14:15], v[52:53], v[140:141], v[14:15] op_sel_hi:[0,1,1]
	v_pk_fma_f32 v[16:17], v[52:53], v[142:143], v[16:17] op_sel_hi:[0,1,1]
	v_pk_fma_f32 v[18:19], v[52:53], v[144:145], v[18:19] op_sel_hi:[0,1,1]
	v_fmac_f32_e32 v27, v52, v146
	v_add_u32_e32 v23, 208, v20
	ds_read2st64_b32 v[130:131], v23 offset1:16
	ds_read2st64_b32 v[132:133], v23 offset0:32 offset1:48
	ds_read2st64_b32 v[134:135], v23 offset0:64 offset1:80
	ds_read2st64_b32 v[136:137], v23 offset0:96 offset1:112
	ds_read2st64_b32 v[138:139], v23 offset0:128 offset1:144
	ds_read2st64_b32 v[140:141], v23 offset0:160 offset1:176
	ds_read2st64_b32 v[142:143], v23 offset0:192 offset1:208
	ds_read2st64_b32 v[144:145], v23 offset0:224 offset1:240
	ds_read_b32 v146, v21 offset:208
	s_waitcnt vmcnt(6) lgkmcnt(9)
	v_pk_fma_f32 v[4:5], v[52:53], v[70:71], v[4:5] op_sel:[1,0,0] op_sel_hi:[1,1,1]
	v_pk_fma_f32 v[6:7], v[52:53], v[72:73], v[6:7] op_sel:[1,0,0] op_sel_hi:[1,1,1]
	v_pk_fma_f32 v[8:9], v[52:53], v[74:75], v[8:9] op_sel:[1,0,0] op_sel_hi:[1,1,1]
	v_pk_fma_f32 v[10:11], v[52:53], v[76:77], v[10:11] op_sel:[1,0,0] op_sel_hi:[1,1,1]
	v_pk_fma_f32 v[12:13], v[52:53], v[78:79], v[12:13] op_sel:[1,0,0] op_sel_hi:[1,1,1]
	v_pk_fma_f32 v[14:15], v[52:53], v[80:81], v[14:15] op_sel:[1,0,0] op_sel_hi:[1,1,1]
	v_pk_fma_f32 v[16:17], v[52:53], v[82:83], v[16:17] op_sel:[1,0,0] op_sel_hi:[1,1,1]
	v_pk_fma_f32 v[18:19], v[52:53], v[84:85], v[18:19] op_sel:[1,0,0] op_sel_hi:[1,1,1]
	v_fmac_f32_e32 v27, v53, v86
	v_add_u32_e32 v26, 216, v20
	ds_read2st64_b32 v[70:71], v26 offset1:16
	ds_read2st64_b32 v[72:73], v26 offset0:32 offset1:48
	ds_read2st64_b32 v[74:75], v26 offset0:64 offset1:80
	ds_read2st64_b32 v[76:77], v26 offset0:96 offset1:112
	ds_read2st64_b32 v[78:79], v26 offset0:128 offset1:144
	ds_read2st64_b32 v[80:81], v26 offset0:160 offset1:176
	ds_read2st64_b32 v[82:83], v26 offset0:192 offset1:208
	ds_read2st64_b32 v[84:85], v26 offset0:224 offset1:240
	ds_read_b32 v86, v21 offset:216
	s_waitcnt vmcnt(5) lgkmcnt(9)
	v_pk_fma_f32 v[4:5], v[54:55], v[130:131], v[4:5] op_sel_hi:[0,1,1]
	v_pk_fma_f32 v[6:7], v[54:55], v[132:133], v[6:7] op_sel_hi:[0,1,1]
	v_pk_fma_f32 v[8:9], v[54:55], v[134:135], v[8:9] op_sel_hi:[0,1,1]
	v_pk_fma_f32 v[10:11], v[54:55], v[136:137], v[10:11] op_sel_hi:[0,1,1]
	v_pk_fma_f32 v[12:13], v[54:55], v[138:139], v[12:13] op_sel_hi:[0,1,1]
	v_pk_fma_f32 v[14:15], v[54:55], v[140:141], v[14:15] op_sel_hi:[0,1,1]
	v_pk_fma_f32 v[16:17], v[54:55], v[142:143], v[16:17] op_sel_hi:[0,1,1]
	v_pk_fma_f32 v[18:19], v[54:55], v[144:145], v[18:19] op_sel_hi:[0,1,1]
	v_fmac_f32_e32 v27, v54, v146
	v_add_u32_e32 v23, 224, v20
	ds_read2st64_b32 v[130:131], v23 offset1:16
	ds_read2st64_b32 v[132:133], v23 offset0:32 offset1:48
	ds_read2st64_b32 v[134:135], v23 offset0:64 offset1:80
	ds_read2st64_b32 v[136:137], v23 offset0:96 offset1:112
	ds_read2st64_b32 v[138:139], v23 offset0:128 offset1:144
	ds_read2st64_b32 v[140:141], v23 offset0:160 offset1:176
	ds_read2st64_b32 v[142:143], v23 offset0:192 offset1:208
	ds_read2st64_b32 v[144:145], v23 offset0:224 offset1:240
	ds_read_b32 v146, v21 offset:224
	s_waitcnt vmcnt(4) lgkmcnt(9)
	v_pk_fma_f32 v[4:5], v[54:55], v[70:71], v[4:5] op_sel:[1,0,0] op_sel_hi:[1,1,1]
	v_pk_fma_f32 v[6:7], v[54:55], v[72:73], v[6:7] op_sel:[1,0,0] op_sel_hi:[1,1,1]
	v_pk_fma_f32 v[8:9], v[54:55], v[74:75], v[8:9] op_sel:[1,0,0] op_sel_hi:[1,1,1]
	v_pk_fma_f32 v[10:11], v[54:55], v[76:77], v[10:11] op_sel:[1,0,0] op_sel_hi:[1,1,1]
	v_pk_fma_f32 v[12:13], v[54:55], v[78:79], v[12:13] op_sel:[1,0,0] op_sel_hi:[1,1,1]
	v_pk_fma_f32 v[14:15], v[54:55], v[80:81], v[14:15] op_sel:[1,0,0] op_sel_hi:[1,1,1]
	v_pk_fma_f32 v[16:17], v[54:55], v[82:83], v[16:17] op_sel:[1,0,0] op_sel_hi:[1,1,1]
	v_pk_fma_f32 v[18:19], v[54:55], v[84:85], v[18:19] op_sel:[1,0,0] op_sel_hi:[1,1,1]
	v_fmac_f32_e32 v27, v55, v86
	v_add_u32_e32 v26, 232, v20
	ds_read2st64_b32 v[70:71], v26 offset1:16
	ds_read2st64_b32 v[72:73], v26 offset0:32 offset1:48
	ds_read2st64_b32 v[74:75], v26 offset0:64 offset1:80
	ds_read2st64_b32 v[76:77], v26 offset0:96 offset1:112
	ds_read2st64_b32 v[78:79], v26 offset0:128 offset1:144
	ds_read2st64_b32 v[80:81], v26 offset0:160 offset1:176
	ds_read2st64_b32 v[82:83], v26 offset0:192 offset1:208
	ds_read2st64_b32 v[84:85], v26 offset0:224 offset1:240
	ds_read_b32 v86, v21 offset:232
	s_waitcnt vmcnt(3) lgkmcnt(9)
	v_pk_fma_f32 v[4:5], v[56:57], v[130:131], v[4:5] op_sel_hi:[0,1,1]
	v_pk_fma_f32 v[6:7], v[56:57], v[132:133], v[6:7] op_sel_hi:[0,1,1]
	v_pk_fma_f32 v[8:9], v[56:57], v[134:135], v[8:9] op_sel_hi:[0,1,1]
	v_pk_fma_f32 v[10:11], v[56:57], v[136:137], v[10:11] op_sel_hi:[0,1,1]
	v_pk_fma_f32 v[12:13], v[56:57], v[138:139], v[12:13] op_sel_hi:[0,1,1]
	v_pk_fma_f32 v[14:15], v[56:57], v[140:141], v[14:15] op_sel_hi:[0,1,1]
	v_pk_fma_f32 v[16:17], v[56:57], v[142:143], v[16:17] op_sel_hi:[0,1,1]
	v_pk_fma_f32 v[18:19], v[56:57], v[144:145], v[18:19] op_sel_hi:[0,1,1]
	v_fmac_f32_e32 v27, v56, v146
	v_add_u32_e32 v23, 240, v20
	ds_read2st64_b32 v[130:131], v23 offset1:16
	ds_read2st64_b32 v[132:133], v23 offset0:32 offset1:48
	ds_read2st64_b32 v[134:135], v23 offset0:64 offset1:80
	ds_read2st64_b32 v[136:137], v23 offset0:96 offset1:112
	ds_read2st64_b32 v[138:139], v23 offset0:128 offset1:144
	ds_read2st64_b32 v[140:141], v23 offset0:160 offset1:176
	ds_read2st64_b32 v[142:143], v23 offset0:192 offset1:208
	ds_read2st64_b32 v[144:145], v23 offset0:224 offset1:240
	ds_read_b32 v146, v21 offset:240
	s_waitcnt vmcnt(2) lgkmcnt(9)
	v_pk_fma_f32 v[4:5], v[56:57], v[70:71], v[4:5] op_sel:[1,0,0] op_sel_hi:[1,1,1]
	v_pk_fma_f32 v[6:7], v[56:57], v[72:73], v[6:7] op_sel:[1,0,0] op_sel_hi:[1,1,1]
	v_pk_fma_f32 v[8:9], v[56:57], v[74:75], v[8:9] op_sel:[1,0,0] op_sel_hi:[1,1,1]
	v_pk_fma_f32 v[10:11], v[56:57], v[76:77], v[10:11] op_sel:[1,0,0] op_sel_hi:[1,1,1]
	v_pk_fma_f32 v[12:13], v[56:57], v[78:79], v[12:13] op_sel:[1,0,0] op_sel_hi:[1,1,1]
	v_pk_fma_f32 v[14:15], v[56:57], v[80:81], v[14:15] op_sel:[1,0,0] op_sel_hi:[1,1,1]
	v_pk_fma_f32 v[16:17], v[56:57], v[82:83], v[16:17] op_sel:[1,0,0] op_sel_hi:[1,1,1]
	v_pk_fma_f32 v[18:19], v[56:57], v[84:85], v[18:19] op_sel:[1,0,0] op_sel_hi:[1,1,1]
	v_fmac_f32_e32 v27, v57, v86
	v_add_u32_e32 v26, 248, v20
	ds_read2st64_b32 v[70:71], v26 offset1:16
	ds_read2st64_b32 v[72:73], v26 offset0:32 offset1:48
	ds_read2st64_b32 v[74:75], v26 offset0:64 offset1:80
	ds_read2st64_b32 v[76:77], v26 offset0:96 offset1:112
	ds_read2st64_b32 v[78:79], v26 offset0:128 offset1:144
	ds_read2st64_b32 v[80:81], v26 offset0:160 offset1:176
	ds_read2st64_b32 v[82:83], v26 offset0:192 offset1:208
	ds_read2st64_b32 v[84:85], v26 offset0:224 offset1:240
	ds_read_b32 v86, v21 offset:248
	s_waitcnt vmcnt(1) lgkmcnt(9)
	v_pk_fma_f32 v[4:5], v[58:59], v[130:131], v[4:5] op_sel_hi:[0,1,1]
	v_pk_fma_f32 v[6:7], v[58:59], v[132:133], v[6:7] op_sel_hi:[0,1,1]
	v_pk_fma_f32 v[8:9], v[58:59], v[134:135], v[8:9] op_sel_hi:[0,1,1]
	v_pk_fma_f32 v[10:11], v[58:59], v[136:137], v[10:11] op_sel_hi:[0,1,1]
	v_pk_fma_f32 v[12:13], v[58:59], v[138:139], v[12:13] op_sel_hi:[0,1,1]
	v_pk_fma_f32 v[14:15], v[58:59], v[140:141], v[14:15] op_sel_hi:[0,1,1]
	v_pk_fma_f32 v[16:17], v[58:59], v[142:143], v[16:17] op_sel_hi:[0,1,1]
	v_pk_fma_f32 v[18:19], v[58:59], v[144:145], v[18:19] op_sel_hi:[0,1,1]
	v_fmac_f32_e32 v27, v58, v146
	s_waitcnt vmcnt(0) lgkmcnt(0)
	v_pk_fma_f32 v[4:5], v[58:59], v[70:71], v[4:5] op_sel:[1,0,0] op_sel_hi:[1,1,1]
	v_pk_fma_f32 v[6:7], v[58:59], v[72:73], v[6:7] op_sel:[1,0,0] op_sel_hi:[1,1,1]
	v_pk_fma_f32 v[8:9], v[58:59], v[74:75], v[8:9] op_sel:[1,0,0] op_sel_hi:[1,1,1]
	v_pk_fma_f32 v[10:11], v[58:59], v[76:77], v[10:11] op_sel:[1,0,0] op_sel_hi:[1,1,1]
	v_pk_fma_f32 v[12:13], v[58:59], v[78:79], v[12:13] op_sel:[1,0,0] op_sel_hi:[1,1,1]
	v_pk_fma_f32 v[14:15], v[58:59], v[80:81], v[14:15] op_sel:[1,0,0] op_sel_hi:[1,1,1]
	v_pk_fma_f32 v[16:17], v[58:59], v[82:83], v[16:17] op_sel:[1,0,0] op_sel_hi:[1,1,1]
	v_pk_fma_f32 v[18:19], v[58:59], v[84:85], v[18:19] op_sel:[1,0,0] op_sel_hi:[1,1,1]
	v_fmac_f32_e32 v27, v59, v86
	v_cndmask_b32_e64 v20, 0, 1, s[4:5]
	v_cmp_ne_u32_e32 vcc, 1, v20
	s_mov_b32 s1, 32
	s_mov_b64 s[4:5], 0
	s_nop 1
	s_and_b64 vcc, exec, vcc
	s_cbranch_vccz .LBB0_519
	ds_bpermute_b32 v2, v67, v4
	ds_bpermute_b32 v3, v67, v5
	ds_bpermute_b32 v20, v67, v6
	ds_bpermute_b32 v21, v67, v7
	ds_bpermute_b32 v22, v67, v8
	ds_bpermute_b32 v23, v67, v9
	ds_bpermute_b32 v24, v67, v10
	ds_bpermute_b32 v25, v67, v11
	ds_bpermute_b32 v26, v67, v12
	ds_bpermute_b32 v28, v67, v13
	ds_bpermute_b32 v29, v67, v14
	ds_bpermute_b32 v30, v67, v15
	ds_bpermute_b32 v31, v67, v16
	ds_bpermute_b32 v32, v67, v17
	ds_bpermute_b32 v33, v67, v18
	ds_bpermute_b32 v34, v67, v19
	ds_bpermute_b32 v35, v67, v27
	s_and_saveexec_b64 s[4:5], s[36:37]
	s_cbranch_execz .LBB0_522
	s_waitcnt lgkmcnt(14)
	v_add_f32_e32 v3, v5, v3
	v_add_f32_e32 v2, v4, v2
	s_waitcnt lgkmcnt(7)
	v_add_f32_e32 v13, v13, v28
	v_add_f32_e32 v12, v12, v26
	v_add_f32_e32 v11, v11, v25
	v_add_f32_e32 v10, v10, v24
	v_add_f32_e32 v9, v9, v23
	v_add_f32_e32 v8, v8, v22
	v_add_f32_e32 v7, v7, v21
	v_add_f32_e32 v6, v6, v20
	ds_write2_b32 v69, v2, v3 offset1:32
	ds_write2_b32 v69, v6, v7 offset0:64 offset1:96
	ds_write2_b32 v69, v8, v9 offset0:128 offset1:160
	ds_write2_b32 v69, v10, v11 offset0:192 offset1:224
	v_add_u32_e32 v2, 0x400, v69
	s_waitcnt lgkmcnt(4)
	v_add_f32_e32 v27, v27, v35
	v_add_f32_e32 v19, v19, v34
	v_add_f32_e32 v18, v18, v33
	v_add_f32_e32 v17, v17, v32
	v_add_f32_e32 v16, v16, v31
	v_add_f32_e32 v15, v15, v30
	v_add_f32_e32 v14, v14, v29
	ds_write2_b32 v2, v12, v13 offset1:32
	ds_write2_b32 v2, v14, v15 offset0:64 offset1:96
	ds_write2_b32 v2, v16, v17 offset0:128 offset1:160
	ds_write2_b32 v2, v18, v19 offset0:192 offset1:224
	ds_write_b32 v69, v27 offset:2048
